# baseline (speedup 1.0000x reference)
; DEVINL float bf2f(u16 h) { return __uint_as_float(((unsigned)h) << 16); }
; DEVINL void ret_out_phase(CParams& p, const Ctx& cx, int l, const GI& gi) {
;     ...
;     const float* gn = p.gn_gain + (size_t)l * DM + h * 256 + fr * 16;
;     float gv[16];
; #pragma unroll
;     for (int q4 = 0; q4 < 4; ++q4) { const float4 g4 = *(const float4*)(gn + q4 * 4); gv[q4 * 4] = g4.x; gv[q4 * 4 + 1] = g4.y; gv[q4 * 4 + 2] = g4.z; gv[q4 * 4 + 3] = g4.w; }
; #pragma unroll
;     for (int j = 0; j < 4; ++j) {
;       float sm = 0.f;
; #pragma unroll
;       for (int et = 0; et < 16; ++et) sm += o[et][j];
; #pragma unroll
;       for (int x = 1; x < 16; x <<= 1) sm += shflx(sm, x, lane);
;       const float mu = sm * (1.f / 256.f);
;       float vs = 0.f;
; #pragma unroll
;       for (int et = 0; et < 16; ++et) { const float d = o[et][j] - mu; vs += d * d; }
; #pragma unroll
;       for (int x = 1; x < 16; x <<= 1) vs += shflx(vs, x, lane);
;       const float rsd = rsqrtf(vs * (1.f / 256.f) + 1e-5f);
;       const size_t ro = (size_t)(row0 + wave * 16 + fq * 4 + j) * DM + h * 256 + fr * 16;
;       const bf16x8 s0 = *(const bf16x8*)(p.sg + ro), s1 = *(const bf16x8*)(p.sg + ro + 8);
;       bf16x8 y0, y1;
; #pragma unroll
;       for (int et = 0; et < 8; ++et) {
;         y0[et] = (short)f2bf(bf2f((u16)s0[et]) * ((o[et][j] - mu) * rsd * gv[et]));
;         y1[et] = (short)f2bf(bf2f((u16)s1[et]) * ((o[et + 8][j] - mu) * rsd * gv[et + 8]));
;       }
;       *(bf16x8*)(p.y + ro) = y0; *(bf16x8*)(p.y + ro + 8) = y1;
;     }
.LBB0_268:
	v_add_u32_e32 v0, s28, v99
	s_waitcnt vmcnt(2)
	v_or_b32_e32 v22, v0, v137
	v_ashrrev_i32_e32 v23, 31, v22
	v_lshlrev_b64 v[2:3], 10, v[22:23]
	v_or3_b32 v2, v2, v98, s96
	v_lshlrev_b64 v[24:25], 1, v[2:3]
	s_waitcnt vmcnt(1)
	v_lshl_add_u64 v[26:27], s[6:7], 0, v[24:25]
	global_load_dwordx4 v[18:21], v[26:27], off offset:16
	v_add_f32_e32 v0, 0, v94
	v_lshlrev_b32_e32 v2, 2, v134
	v_add_f32_e32 v3, 0, v95
	v_add_f32_e32 v4, v0, v90
	v_bfrev_b32_e32 v0, 0.5
	v_mov_b32_e32 v104, v94
	v_bitop3_b32 v99, v2, 4, v0 bitop3:0x6c
	v_bitop3_b32 v94, v2, 8, v0 bitop3:0x6c
	v_bitop3_b32 v23, v2, 16, v0 bitop3:0x6c
	v_bitop3_b32 v0, v2, 32, v0 bitop3:0x6c
	v_add_f32_e32 v2, v3, v91
	v_add_f32_e32 v3, v4, v86
	v_add_f32_e32 v11, v3, v78
	v_add_f32_e32 v11, v11, v70
	v_add_f32_e32 v11, v11, v62
	v_add_f32_e32 v11, v11, v54
	v_add_f32_e32 v11, v11, v46
	v_add_f32_e32 v11, v11, v82
	v_add_f32_e32 v11, v11, v74
	v_add_f32_e32 v11, v11, v66
	v_add_f32_e32 v11, v11, v58
	v_add_f32_e32 v11, v11, v50
	v_add_f32_e32 v11, v11, v42
	v_add_f32_e32 v11, v11, v38
	v_add_f32_e32 v11, v11, v34
	s_nop 1
	v_mov_b32_dpp v12, v11 quad_perm:[1,0,3,2] row_mask:0xf bank_mask:0xf
	v_add_f32_e32 v10, v2, v87
	v_add_f32_e32 v10, v10, v79
	v_add_f32_e32 v10, v10, v71
	v_add_f32_e32 v10, v10, v63
	s_waitcnt lgkmcnt(0)
	v_add_f32_e32 v11, v11, v12
	s_nop 1
	v_mov_b32_dpp v12, v11 quad_perm:[2,3,0,1] row_mask:0xf bank_mask:0xf
	v_add_f32_e32 v10, v10, v55
	v_add_f32_e32 v10, v10, v47
	v_add_f32_e32 v10, v10, v83
	v_add_f32_e32 v10, v10, v75
	s_waitcnt lgkmcnt(0)
	v_add_f32_e32 v11, v11, v12
	v_add_f32_e32 v10, v10, v67
	ds_bpermute_b32 v12, v23, v11
	v_add_f32_e32 v10, v10, v59
	s_lshl_b32 s16, s27, 10
	v_add_f32_e32 v10, v10, v51
	s_add_u32 s16, s24, s16
	v_add_f32_e32 v10, v10, v43
	v_lshlrev_b32_e32 v14, 2, v98
	s_addc_u32 s17, s25, 0
	v_add_f32_e32 v10, v10, v39
	v_mov_b32_e32 v101, v42
	v_mov_b32_e32 v103, v34
	global_load_dwordx4 v[2:5], v14, s[16:17] offset:48
	global_load_dwordx4 v[6:9], v14, s[16:17] offset:32
	v_add_f32_e32 v34, v10, v35
	s_waitcnt lgkmcnt(0)
	v_add_f32_e32 v42, v11, v12
	global_load_dwordx4 v[10:13], v14, s[16:17] offset:16
	s_nop 0
	global_load_dwordx4 v[14:17], v14, s[16:17]
	s_nop 0
	global_load_dwordx4 v[26:29], v[26:27], off
	v_mov_b32_e32 v102, v38
	ds_bpermute_b32 v38, v99, v34
	s_waitcnt vmcnt(6)
	v_mov_b32_e32 v33, v58
	v_mov_b32_e32 v100, v50
	ds_bpermute_b32 v50, v0, v42
	v_mov_b32_e32 v105, v90
	s_waitcnt lgkmcnt(1)
	v_add_f32_e32 v38, v34, v38
	s_nop 1
	v_mov_b32_dpp v58, v38 quad_perm:[2,3,0,1] row_mask:0xf bank_mask:0xf
	v_mov_b32_e32 v90, v95
	s_waitcnt lgkmcnt(1)
	v_add_f32_e32 v34, v42, v50
	v_mul_f32_e32 v34, 0x3b800000, v34
	v_mov_b32_e32 v30, v82
	s_waitcnt lgkmcnt(0)
	v_add_f32_e32 v38, v38, v58
	s_nop 1
	v_mov_b32_dpp v42, v38 row_shl:4 row_mask:0xf bank_mask:0x5
	v_mov_b32_dpp v42, v38 row_shr:4 row_mask:0xf bank_mask:0xa
	v_mov_b32_e32 v31, v74
	v_pk_add_f32 v[104:105], v[104:105], v[34:35] op_sel_hi:[1,0] neg_lo:[0,1] neg_hi:[0,1]
	v_mov_b32_e32 v74, v83
	v_mov_b32_e32 v32, v66
	s_waitcnt lgkmcnt(0)
	v_add_f32_e32 v38, v38, v42
	ds_bpermute_b32 v42, v0, v38
	v_pk_add_f32 v[30:31], v[30:31], v[34:35] op_sel_hi:[1,0] neg_lo:[0,1] neg_hi:[0,1]
	v_pk_add_f32 v[32:33], v[32:33], v[34:35] op_sel_hi:[1,0] neg_lo:[0,1] neg_hi:[0,1]
	v_pk_add_f32 v[100:101], v[100:101], v[34:35] op_sel_hi:[1,0] neg_lo:[0,1] neg_hi:[0,1]
	v_pk_add_f32 v[102:103], v[102:103], v[34:35] op_sel_hi:[1,0] neg_lo:[0,1] neg_hi:[0,1]
	v_mov_b32_e32 v58, v67
	v_pk_mul_f32 v[106:107], v[32:33], v[32:33]
	s_waitcnt vmcnt(5)
	v_and_b32_e32 v113, 0xffff0000, v18
	v_lshlrev_b32_e32 v112, 16, v18
	v_and_b32_e32 v115, 0xffff0000, v19
	v_lshlrev_b32_e32 v114, 16, v19
	v_mov_b32_e32 v18, v86
	v_mov_b32_e32 v19, v78
	v_pk_add_f32 v[116:117], v[18:19], v[34:35] op_sel_hi:[1,0] neg_lo:[0,1] neg_hi:[0,1]
	v_mov_b32_e32 v18, v70
	v_mov_b32_e32 v19, v62
	v_pk_add_f32 v[118:119], v[18:19], v[34:35] op_sel_hi:[1,0] neg_lo:[0,1] neg_hi:[0,1]
	v_mov_b32_e32 v18, v54
	v_mov_b32_e32 v19, v46
	v_pk_add_f32 v[120:121], v[18:19], v[34:35] op_sel_hi:[1,0] neg_lo:[0,1] neg_hi:[0,1]
	s_waitcnt lgkmcnt(0)
	v_add_f32_e32 v18, v38, v42
	v_mul_f32_e32 v18, 0x3b800000, v18
	v_pk_add_f32 v[82:83], v[90:91], v[18:19] op_sel_hi:[1,0] neg_lo:[0,1] neg_hi:[0,1]
	v_mov_b32_e32 v78, v87
	v_mov_b32_e32 v86, v83
	v_mov_b32_e32 v87, v105
	v_pk_add_f32 v[78:79], v[78:79], v[18:19] op_sel_hi:[1,0] neg_lo:[0,1] neg_hi:[0,1]
	v_mov_b32_e32 v62, v71
	v_mov_b32_e32 v70, v82
	v_mov_b32_e32 v71, v104
	v_pk_mul_f32 v[86:87], v[86:87], v[86:87]
	v_pk_add_f32 v[62:63], v[62:63], v[18:19] op_sel_hi:[1,0] neg_lo:[0,1] neg_hi:[0,1]
	v_pk_fma_f32 v[70:71], v[70:71], v[70:71], v[86:87]
	v_mov_b32_e32 v86, v78
	v_mov_b32_e32 v87, v116
	v_mov_b32_e32 v90, v79
	v_mov_b32_e32 v91, v117
	v_pk_fma_f32 v[70:71], v[86:87], v[86:87], v[70:71]
	v_mov_b32_e32 v46, v55
	v_pk_fma_f32 v[70:71], v[90:91], v[90:91], v[70:71]
	v_mov_b32_e32 v86, v62
	v_mov_b32_e32 v87, v118
	v_pk_add_f32 v[46:47], v[46:47], v[18:19] op_sel_hi:[1,0] neg_lo:[0,1] neg_hi:[0,1]
	v_mov_b32_e32 v90, v63
	v_mov_b32_e32 v91, v119
	v_pk_fma_f32 v[70:71], v[86:87], v[86:87], v[70:71]
	v_mov_b32_e32 v86, v46
	v_pk_fma_f32 v[70:71], v[90:91], v[90:91], v[70:71]
	v_mov_b32_e32 v87, v120
	v_pk_add_f32 v[74:75], v[74:75], v[18:19] op_sel_hi:[1,0] neg_lo:[0,1] neg_hi:[0,1]
	v_mov_b32_e32 v42, v51
	v_mov_b32_e32 v34, v39
	v_mov_b32_e32 v90, v47
	v_mov_b32_e32 v91, v121
	v_pk_fma_f32 v[70:71], v[86:87], v[86:87], v[70:71]
	v_pk_add_f32 v[58:59], v[58:59], v[18:19] op_sel_hi:[1,0] neg_lo:[0,1] neg_hi:[0,1]
	v_pk_add_f32 v[42:43], v[42:43], v[18:19] op_sel_hi:[1,0] neg_lo:[0,1] neg_hi:[0,1]
	v_pk_add_f32 v[34:35], v[34:35], v[18:19] op_sel_hi:[1,0] neg_lo:[0,1] neg_hi:[0,1]
	v_mov_b32_e32 v18, v74
	v_mov_b32_e32 v19, v30
	v_pk_fma_f32 v[70:71], v[90:91], v[90:91], v[70:71]
	v_pk_mul_f32 v[66:67], v[58:59], v[58:59]
	v_mov_b32_e32 v54, v75
	v_mov_b32_e32 v55, v31
	v_pk_fma_f32 v[18:19], v[18:19], v[18:19], v[70:71]
	v_pk_mul_f32 v[108:109], v[100:101], v[100:101]
	v_pk_fma_f32 v[18:19], v[54:55], v[54:55], v[18:19]
	v_mov_b32_e32 v54, v66
	v_mov_b32_e32 v55, v106
	v_pk_mul_f32 v[50:51], v[42:43], v[42:43]
	v_pk_add_f32 v[18:19], v[54:55], v[18:19]
	v_mov_b32_e32 v106, v67
	v_pk_add_f32 v[18:19], v[106:107], v[18:19]
	v_mov_b32_e32 v54, v50
	v_mov_b32_e32 v55, v108
	v_pk_mul_f32 v[110:111], v[102:103], v[102:103]
	v_pk_mul_f32 v[38:39], v[34:35], v[34:35]
	v_pk_add_f32 v[18:19], v[54:55], v[18:19]
	v_mov_b32_e32 v108, v51
	v_pk_add_f32 v[18:19], v[108:109], v[18:19]
	v_mov_b32_e32 v50, v38
	v_mov_b32_e32 v51, v110
	v_pk_add_f32 v[18:19], v[50:51], v[18:19]
	v_mov_b32_e32 v110, v39
	v_pk_add_f32 v[18:19], v[110:111], v[18:19]
	ds_bpermute_b32 v39, v99, v19
	ds_bpermute_b32 v38, v99, v18
	s_waitcnt vmcnt(0)
; DEVINL float bf2f(u16 h) { return __uint_as_float(((unsigned)h) << 16); }
; DEVINL void ret_out_phase(CParams& p, const Ctx& cx, int l, const GI& gi) {
;     ...
; #pragma unroll
;     for (int j = 0; j < 4; ++j) {
;       float sm = 0.f;
; #pragma unroll
;       for (int et = 0; et < 16; ++et) sm += o[et][j];
; #pragma unroll
;       for (int x = 1; x < 16; x <<= 1) sm += shflx(sm, x, lane);
;       const float mu = sm * (1.f / 256.f);
;       float vs = 0.f;
; #pragma unroll
;       for (int et = 0; et < 16; ++et) { const float d = o[et][j] - mu; vs += d * d; }
; #pragma unroll
;       for (int x = 1; x < 16; x <<= 1) vs += shflx(vs, x, lane);
;       const float rsd = rsqrtf(vs * (1.f / 256.f) + 1e-5f);
;       const size_t ro = (size_t)(row0 + wave * 16 + fq * 4 + j) * DM + h * 256 + fr * 16;
;       const bf16x8 s0 = *(const bf16x8*)(p.sg + ro), s1 = *(const bf16x8*)(p.sg + ro + 8);
;       bf16x8 y0, y1;
; #pragma unroll
;       for (int et = 0; et < 8; ++et) {
;         y0[et] = (short)f2bf(bf2f((u16)s0[et]) * ((o[et][j] - mu) * rsd * gv[et]));
;         y1[et] = (short)f2bf(bf2f((u16)s1[et]) * ((o[et + 8][j] - mu) * rsd * gv[et + 8]));
;       }
;       *(bf16x8*)(p.y + ro) = y0; *(bf16x8*)(p.y + ro + 8) = y1;
;     }
	v_and_b32_e32 v55, 0xffff0000, v26
	v_lshlrev_b32_e32 v54, 16, v26
	v_and_b32_e32 v67, 0xffff0000, v27
	v_lshlrev_b32_e32 v66, 16, v27
	s_waitcnt lgkmcnt(0)
	v_pk_add_f32 v[18:19], v[18:19], v[38:39]
	ds_bpermute_b32 v39, v94, v19
	ds_bpermute_b32 v38, v94, v18
	v_and_b32_e32 v51, 0xffff0000, v20
	v_lshlrev_b32_e32 v50, 16, v20
	v_lshl_add_u64 v[90:91], s[14:15], 0, v[24:25]
	v_or_b32_e32 v24, 1, v22
	s_waitcnt lgkmcnt(0)
	v_pk_add_f32 v[18:19], v[18:19], v[38:39]
	ds_bpermute_b32 v27, v23, v19
	ds_bpermute_b32 v26, v23, v18
	v_and_b32_e32 v39, 0xffff0000, v21
	v_lshlrev_b32_e32 v38, 16, v21
	v_ashrrev_i32_e32 v25, 31, v24
	s_mov_b32 s16, 0x3727c5ac
	s_waitcnt lgkmcnt(0)
	v_pk_add_f32 v[18:19], v[18:19], v[26:27]
	ds_bpermute_b32 v21, v0, v19
	ds_bpermute_b32 v20, v0, v18
	v_lshlrev_b64 v[26:27], 10, v[24:25]
	v_mov_b64_e32 v[24:25], s[16:17]
	v_or3_b32 v26, v26, v98, s96
	v_lshlrev_b64 v[108:109], 1, v[26:27]
	s_waitcnt lgkmcnt(0)
	v_pk_add_f32 v[18:19], v[18:19], v[20:21]
	v_and_b32_e32 v71, 0xffff0000, v28
	v_pk_fma_f32 v[106:107], v[18:19], s[38:39], v[24:25] op_sel_hi:[1,0,0]
	v_lshlrev_b32_e32 v70, 16, v28
	v_mul_f32_e32 v18, 0x4b800000, v107
	v_cmp_gt_f32_e32 vcc, s35, v107
	v_and_b32_e32 v87, 0xffff0000, v29
	v_lshlrev_b32_e32 v86, 16, v29
	v_cndmask_b32_e32 v18, v107, v18, vcc
	v_rsq_f32_e32 v18, v18
	v_lshl_add_u64 v[110:111], s[6:7], 0, v[108:109]
	s_add_i32 s26, s26, s33
	s_cmp_ge_i32 s26, s22
	v_mul_f32_e32 v19, 0x45800000, v18
	v_cndmask_b32_e32 v122, v18, v19, vcc
	v_pk_mul_f32 v[20:21], v[30:31], v[122:123] op_sel_hi:[1,0]
	v_pk_mul_f32 v[18:19], v[104:105], v[122:123] op_sel_hi:[1,0]
	v_pk_mul_f32 v[20:21], v[6:7], v[20:21]
	v_pk_mul_f32 v[18:19], v[14:15], v[18:19]
	v_pk_mul_f32 v[20:21], v[20:21], v[112:113]
	v_pk_mul_f32 v[18:19], v[18:19], v[54:55]
	v_cvt_pk_bf16_f32 v26, v20, v21
	v_pk_mul_f32 v[20:21], v[116:117], v[122:123] op_sel_hi:[1,0]
	v_cvt_pk_bf16_f32 v18, v18, v19
	v_pk_mul_f32 v[20:21], v[16:17], v[20:21]
	v_pk_mul_f32 v[30:31], v[120:121], v[122:123] op_sel_hi:[1,0]
	v_pk_mul_f32 v[20:21], v[20:21], v[66:67]
	v_pk_mul_f32 v[30:31], v[12:13], v[30:31]
	v_cvt_pk_bf16_f32 v19, v20, v21
	v_pk_mul_f32 v[20:21], v[32:33], v[122:123] op_sel_hi:[1,0]
	v_pk_mul_f32 v[30:31], v[30:31], v[86:87]
	v_pk_mul_f32 v[20:21], v[8:9], v[20:21]
	v_pk_mul_f32 v[28:29], v[100:101], v[122:123] op_sel_hi:[1,0]
	v_pk_mul_f32 v[20:21], v[20:21], v[114:115]
	v_pk_mul_f32 v[28:29], v[2:3], v[28:29]
	v_cvt_pk_bf16_f32 v27, v20, v21
	v_pk_mul_f32 v[20:21], v[118:119], v[122:123] op_sel_hi:[1,0]
	v_pk_mul_f32 v[28:29], v[28:29], v[50:51]
	v_pk_mul_f32 v[20:21], v[10:11], v[20:21]
	v_cvt_pk_bf16_f32 v28, v28, v29
	v_pk_mul_f32 v[20:21], v[20:21], v[70:71]
	v_cmp_gt_f32_e32 vcc, s35, v106
	v_cvt_pk_bf16_f32 v20, v20, v21
	v_cvt_pk_bf16_f32 v21, v30, v31
	v_pk_mul_f32 v[30:31], v[102:103], v[122:123] op_sel_hi:[1,0]
	s_nop 0
	v_pk_mul_f32 v[30:31], v[4:5], v[30:31]
	s_nop 0
	v_pk_mul_f32 v[30:31], v[30:31], v[38:39]
	s_nop 0
	v_cvt_pk_bf16_f32 v29, v30, v31
	global_store_dwordx4 v[90:91], v[18:21], off
	global_store_dwordx4 v[90:91], v[26:29], off offset:16
	global_load_dwordx4 v[18:21], v[110:111], off offset:16
	s_nop 0
	global_load_dwordx4 v[26:29], v[110:111], off
	s_waitcnt vmcnt(1)
	v_and_b32_e32 v39, 0xffff0000, v20
	v_lshlrev_b32_e32 v38, 16, v20
	v_mul_f32_e32 v20, 0x4b800000, v106
	v_cndmask_b32_e32 v20, v106, v20, vcc
	v_rsq_f32_e32 v20, v20
	v_and_b32_e32 v67, 0xffff0000, v21
	v_lshlrev_b32_e32 v66, 16, v21
	v_and_b32_e32 v31, 0xffff0000, v18
	v_mul_f32_e32 v21, 0x45800000, v20
	v_cndmask_b32_e32 v86, v20, v21, vcc
	v_pk_mul_f32 v[20:21], v[82:83], v[86:87] op_sel_hi:[1,0]
	v_lshlrev_b32_e32 v30, 16, v18
	v_and_b32_e32 v33, 0xffff0000, v19
	v_lshlrev_b32_e32 v32, 16, v19
	s_waitcnt vmcnt(0)
	v_and_b32_e32 v19, 0xffff0000, v26
	v_lshlrev_b32_e32 v18, 16, v26
	v_pk_mul_f32 v[20:21], v[14:15], v[20:21]
	v_and_b32_e32 v51, 0xffff0000, v27
	v_pk_mul_f32 v[18:19], v[20:21], v[18:19]
	v_pk_mul_f32 v[20:21], v[74:75], v[86:87] op_sel_hi:[1,0]
	v_lshlrev_b32_e32 v50, 16, v27
	v_pk_mul_f32 v[20:21], v[6:7], v[20:21]
	v_cvt_pk_bf16_f32 v18, v18, v19
	v_pk_mul_f32 v[20:21], v[20:21], v[30:31]
	v_pk_mul_f32 v[30:31], v[46:47], v[86:87] op_sel_hi:[1,0]
	v_cvt_pk_bf16_f32 v26, v20, v21
	v_pk_mul_f32 v[20:21], v[78:79], v[86:87] op_sel_hi:[1,0]
	v_and_b32_e32 v55, 0xffff0000, v28
	v_pk_mul_f32 v[20:21], v[16:17], v[20:21]
	v_lshlrev_b32_e32 v54, 16, v28
	v_pk_mul_f32 v[20:21], v[20:21], v[50:51]
	v_and_b32_e32 v71, 0xffff0000, v29
	v_cvt_pk_bf16_f32 v19, v20, v21
	v_pk_mul_f32 v[20:21], v[58:59], v[86:87] op_sel_hi:[1,0]
	v_lshlrev_b32_e32 v70, 16, v29
	v_pk_mul_f32 v[20:21], v[8:9], v[20:21]
	v_pk_mul_f32 v[30:31], v[12:13], v[30:31]
	v_pk_mul_f32 v[20:21], v[20:21], v[32:33]
	v_pk_mul_f32 v[30:31], v[30:31], v[70:71]
	v_cvt_pk_bf16_f32 v27, v20, v21
	v_pk_mul_f32 v[20:21], v[62:63], v[86:87] op_sel_hi:[1,0]
	v_pk_mul_f32 v[28:29], v[42:43], v[86:87] op_sel_hi:[1,0]
	v_pk_mul_f32 v[20:21], v[10:11], v[20:21]
	v_pk_mul_f32 v[28:29], v[2:3], v[28:29]
	v_pk_mul_f32 v[20:21], v[20:21], v[54:55]
	v_pk_mul_f32 v[28:29], v[28:29], v[38:39]
	v_cvt_pk_bf16_f32 v20, v20, v21
	v_cvt_pk_bf16_f32 v21, v30, v31
	v_pk_mul_f32 v[30:31], v[34:35], v[86:87] op_sel_hi:[1,0]
	v_cvt_pk_bf16_f32 v28, v28, v29
	v_pk_mul_f32 v[30:31], v[4:5], v[30:31]
	v_mov_b32_e32 v32, v68
	v_pk_mul_f32 v[30:31], v[30:31], v[66:67]
	v_mov_b32_e32 v33, v60
	v_cvt_pk_bf16_f32 v29, v30, v31
	v_lshl_add_u64 v[30:31], s[14:15], 0, v[108:109]
	global_store_dwordx4 v[30:31], v[18:21], off
	global_store_dwordx4 v[30:31], v[26:29], off offset:16
	v_add_f32_e32 v30, 0, v96
	v_or_b32_e32 v18, 2, v22
	v_ashrrev_i32_e32 v19, 31, v18
	v_lshlrev_b64 v[18:19], 10, v[18:19]
	v_or3_b32 v18, v18, v98, s96
	v_lshlrev_b64 v[26:27], 1, v[18:19]
	v_lshl_add_u64 v[28:29], s[6:7], 0, v[26:27]
	global_load_dwordx4 v[18:21], v[28:29], off offset:16
	global_load_dwordx4 v[100:103], v[28:29], off
	v_add_f32_e32 v30, v30, v92
	v_add_f32_e32 v30, v30, v88
	v_add_f32_e32 v30, v30, v80
	v_add_f32_e32 v30, v30, v72
	v_add_f32_e32 v30, v30, v64
	v_add_f32_e32 v30, v30, v56
	v_add_f32_e32 v30, v30, v48
	v_add_f32_e32 v30, v30, v84
	v_add_f32_e32 v30, v30, v76
	v_add_f32_e32 v30, v30, v68
	v_add_f32_e32 v30, v30, v60
	v_add_f32_e32 v30, v30, v52
	v_add_f32_e32 v30, v30, v44
	v_add_f32_e32 v30, v30, v40
	v_add_f32_e32 v30, v30, v36
	s_nop 1
	v_mov_b32_dpp v31, v30 quad_perm:[1,0,3,2] row_mask:0xf bank_mask:0xf
	v_mov_b32_e32 v29, v76
	v_mov_b32_e32 v50, v40
	v_mov_b32_e32 v51, v36
	v_mov_b32_e32 v58, v96
	s_waitcnt lgkmcnt(0)
; DEVINL float bf2f(u16 h) { return __uint_as_float(((unsigned)h) << 16); }
; DEVINL void ret_out_phase(CParams& p, const Ctx& cx, int l, const GI& gi) {
;     ...
; #pragma unroll
;     for (int j = 0; j < 4; ++j) {
;       float sm = 0.f;
; #pragma unroll
;       for (int et = 0; et < 16; ++et) sm += o[et][j];
; #pragma unroll
;       for (int x = 1; x < 16; x <<= 1) sm += shflx(sm, x, lane);
;       const float mu = sm * (1.f / 256.f);
;       float vs = 0.f;
; #pragma unroll
;       for (int et = 0; et < 16; ++et) { const float d = o[et][j] - mu; vs += d * d; }
; #pragma unroll
;       for (int x = 1; x < 16; x <<= 1) vs += shflx(vs, x, lane);
;       const float rsd = rsqrtf(vs * (1.f / 256.f) + 1e-5f);
;       const size_t ro = (size_t)(row0 + wave * 16 + fq * 4 + j) * DM + h * 256 + fr * 16;
;       const bf16x8 s0 = *(const bf16x8*)(p.sg + ro), s1 = *(const bf16x8*)(p.sg + ro + 8);
;       bf16x8 y0, y1;
; #pragma unroll
;       for (int et = 0; et < 8; ++et) {
;         y0[et] = (short)f2bf(bf2f((u16)s0[et]) * ((o[et][j] - mu) * rsd * gv[et]));
;         y1[et] = (short)f2bf(bf2f((u16)s1[et]) * ((o[et + 8][j] - mu) * rsd * gv[et + 8]));
;       }
;       *(bf16x8*)(p.y + ro) = y0; *(bf16x8*)(p.y + ro + 8) = y1;
;     }
	v_add_f32_e32 v30, v30, v31
	s_nop 1
	v_mov_b32_dpp v31, v30 quad_perm:[2,3,0,1] row_mask:0xf bank_mask:0xf
	v_mov_b32_e32 v59, v92
	v_mov_b32_e32 v62, v88
	v_mov_b32_e32 v63, v80
	v_mov_b32_e32 v66, v72
	s_waitcnt lgkmcnt(0)
	v_add_f32_e32 v30, v30, v31
	s_nop 1
	v_mov_b32_dpp v31, v30 row_shl:4 row_mask:0xf bank_mask:0x5
	v_mov_b32_dpp v31, v30 row_shr:4 row_mask:0xf bank_mask:0xa
	v_mov_b32_e32 v67, v64
	v_mov_b32_e32 v70, v56
	v_mov_b32_e32 v71, v48
	v_mov_b32_e32 v76, v85
	s_waitcnt lgkmcnt(0)
	v_add_f32_e32 v30, v30, v31
	ds_bpermute_b32 v31, v0, v30
	v_mov_b32_e32 v92, v97
	v_mov_b32_e32 v80, v89
	v_mov_b32_e32 v64, v73
	v_mov_b32_e32 v60, v69
	s_waitcnt lgkmcnt(0)
	v_add_f32_e32 v28, v30, v31
	v_mul_f32_e32 v38, 0x3b800000, v28
	v_mov_b32_e32 v28, v84
	v_pk_add_f32 v[30:31], v[28:29], v[38:39] op_sel_hi:[1,0] neg_lo:[0,1] neg_hi:[0,1]
	v_pk_add_f32 v[32:33], v[32:33], v[38:39] op_sel_hi:[1,0] neg_lo:[0,1] neg_hi:[0,1]
	v_mov_b32_e32 v48, v57
	v_pk_mul_f32 v[42:43], v[32:33], v[32:33]
	v_or_b32_e32 v22, 3, v22
	s_waitcnt vmcnt(1)
	v_and_b32_e32 v29, 0xffff0000, v18
	v_lshlrev_b32_e32 v28, 16, v18
	v_and_b32_e32 v35, 0xffff0000, v19
	v_lshlrev_b32_e32 v34, 16, v19
	v_mov_b32_e32 v18, v52
	v_mov_b32_e32 v19, v44
	v_pk_add_f32 v[18:19], v[18:19], v[38:39] op_sel_hi:[1,0] neg_lo:[0,1] neg_hi:[0,1]
	v_add_f32_e32 v39, 0, v97
	v_add_f32_e32 v39, v39, v93
	v_add_f32_e32 v39, v39, v89
	v_add_f32_e32 v39, v39, v81
	v_add_f32_e32 v39, v39, v73
	v_add_f32_e32 v39, v39, v65
	v_add_f32_e32 v39, v39, v57
	v_add_f32_e32 v39, v39, v49
	v_add_f32_e32 v39, v39, v85
	v_add_f32_e32 v39, v39, v77
	v_add_f32_e32 v39, v39, v69
	v_add_f32_e32 v39, v39, v61
	v_add_f32_e32 v39, v39, v53
	v_add_f32_e32 v39, v39, v45
	v_add_f32_e32 v39, v39, v41
	v_add_f32_e32 v39, v39, v37
	ds_bpermute_b32 v44, v99, v39
	v_pk_add_f32 v[50:51], v[50:51], v[38:39] op_sel_hi:[1,0] neg_lo:[0,1] neg_hi:[0,1]
	v_mov_b32_e32 v57, v31
	v_pk_mul_f32 v[46:47], v[18:19], v[18:19]
	v_pk_mul_f32 v[54:55], v[50:51], v[50:51]
	s_waitcnt lgkmcnt(0)
	v_add_f32_e32 v36, v39, v44
	s_nop 1
	v_mov_b32_dpp v39, v36 quad_perm:[2,3,0,1] row_mask:0xf bank_mask:0xf
	v_mov_b32_e32 v44, v53
	s_waitcnt lgkmcnt(0)
	v_add_f32_e32 v36, v36, v39
	v_pk_add_f32 v[58:59], v[58:59], v[38:39] op_sel_hi:[1,0] neg_lo:[0,1] neg_hi:[0,1]
	s_nop 1
	v_mov_b32_dpp v39, v36 row_shl:4 row_mask:0xf bank_mask:0x5
	v_mov_b32_dpp v39, v36 row_shr:4 row_mask:0xf bank_mask:0xa
	v_mov_b32_e32 v73, v58
	s_waitcnt lgkmcnt(0)
	v_add_f32_e32 v36, v36, v39
	s_nop 1
	v_mov_b32_dpp v40, v36 row_ror:8 row_mask:0xf bank_mask:0xf
	v_pk_add_f32 v[62:63], v[62:63], v[38:39] op_sel_hi:[1,0] neg_lo:[0,1] neg_hi:[0,1]
	v_pk_add_f32 v[66:67], v[66:67], v[38:39] op_sel_hi:[1,0] neg_lo:[0,1] neg_hi:[0,1]
	v_pk_add_f32 v[38:39], v[70:71], v[38:39] op_sel_hi:[1,0] neg_lo:[0,1] neg_hi:[0,1]
	v_mov_b32_e32 v83, v63
	s_waitcnt lgkmcnt(0)
	v_add_f32_e32 v36, v36, v40
	v_mul_f32_e32 v40, 0x3b800000, v36
	v_pk_add_f32 v[70:71], v[76:77], v[40:41] op_sel_hi:[1,0] neg_lo:[0,1] neg_hi:[0,1]
	v_pk_add_f32 v[76:77], v[92:93], v[40:41] op_sel_hi:[1,0] neg_lo:[0,1] neg_hi:[0,1]
	v_pk_add_f32 v[78:79], v[80:81], v[40:41] op_sel_hi:[1,0] neg_lo:[0,1] neg_hi:[0,1]
	v_mov_b32_e32 v80, v77
	v_mov_b32_e32 v81, v59
	v_mov_b32_e32 v72, v76
	v_pk_mul_f32 v[80:81], v[80:81], v[80:81]
	v_pk_add_f32 v[64:65], v[64:65], v[40:41] op_sel_hi:[1,0] neg_lo:[0,1] neg_hi:[0,1]
	v_pk_fma_f32 v[72:73], v[72:73], v[72:73], v[80:81]
	v_mov_b32_e32 v80, v78
	v_mov_b32_e32 v81, v62
	v_mov_b32_e32 v82, v79
	v_pk_fma_f32 v[72:73], v[80:81], v[80:81], v[72:73]
	v_mov_b32_e32 v36, v41
	v_pk_fma_f32 v[72:73], v[82:83], v[82:83], v[72:73]
	v_mov_b32_e32 v80, v64
	v_mov_b32_e32 v81, v66
	v_pk_add_f32 v[60:61], v[60:61], v[40:41] op_sel_hi:[1,0] neg_lo:[0,1] neg_hi:[0,1]
	v_pk_add_f32 v[44:45], v[44:45], v[40:41] op_sel_hi:[1,0] neg_lo:[0,1] neg_hi:[0,1]
	v_pk_add_f32 v[36:37], v[36:37], v[40:41] op_sel_hi:[1,0] neg_lo:[0,1] neg_hi:[0,1]
	v_pk_add_f32 v[40:41], v[48:49], v[40:41] op_sel_hi:[1,0] neg_lo:[0,1] neg_hi:[0,1]
	v_mov_b32_e32 v82, v65
	v_mov_b32_e32 v83, v67
	v_pk_fma_f32 v[72:73], v[80:81], v[80:81], v[72:73]
	v_mov_b32_e32 v80, v40
	v_pk_fma_f32 v[72:73], v[82:83], v[82:83], v[72:73]
	v_mov_b32_e32 v81, v38
	v_mov_b32_e32 v82, v41
	v_mov_b32_e32 v83, v39
	v_pk_fma_f32 v[72:73], v[80:81], v[80:81], v[72:73]
	v_mov_b32_e32 v48, v70
	v_mov_b32_e32 v49, v30
	v_pk_fma_f32 v[72:73], v[82:83], v[82:83], v[72:73]
	v_pk_mul_f32 v[68:69], v[60:61], v[60:61]
	v_mov_b32_e32 v56, v71
	v_pk_fma_f32 v[48:49], v[48:49], v[48:49], v[72:73]
	v_pk_mul_f32 v[52:53], v[44:45], v[44:45]
	v_pk_fma_f32 v[48:49], v[56:57], v[56:57], v[48:49]
	v_mov_b32_e32 v56, v68
	v_mov_b32_e32 v57, v42
	v_pk_add_f32 v[48:49], v[56:57], v[48:49]
	v_mov_b32_e32 v42, v69
	v_pk_add_f32 v[42:43], v[42:43], v[48:49]
	v_mov_b32_e32 v48, v52
	v_mov_b32_e32 v49, v46
	v_pk_mul_f32 v[74:75], v[36:37], v[36:37]
	v_pk_add_f32 v[42:43], v[48:49], v[42:43]
	v_mov_b32_e32 v46, v53
	v_pk_add_f32 v[42:43], v[46:47], v[42:43]
	v_mov_b32_e32 v46, v74
	v_mov_b32_e32 v47, v54
	v_pk_add_f32 v[42:43], v[46:47], v[42:43]
	v_mov_b32_e32 v54, v75
	v_pk_add_f32 v[42:43], v[54:55], v[42:43]
	ds_bpermute_b32 v47, v99, v43
	ds_bpermute_b32 v46, v99, v42
	v_and_b32_e32 v49, 0xffff0000, v20
	v_lshlrev_b32_e32 v48, 16, v20
	v_and_b32_e32 v69, 0xffff0000, v21
	v_lshlrev_b32_e32 v68, 16, v21
	s_waitcnt lgkmcnt(0)
; DEVINL float bf2f(u16 h) { return __uint_as_float(((unsigned)h) << 16); }
; DEVINL void ret_out_phase(CParams& p, const Ctx& cx, int l, const GI& gi) {
;     ...
; #pragma unroll
;     for (int j = 0; j < 4; ++j) {
;       float sm = 0.f;
; #pragma unroll
;       for (int et = 0; et < 16; ++et) sm += o[et][j];
; #pragma unroll
;       for (int x = 1; x < 16; x <<= 1) sm += shflx(sm, x, lane);
;       const float mu = sm * (1.f / 256.f);
;       float vs = 0.f;
; #pragma unroll
;       for (int et = 0; et < 16; ++et) { const float d = o[et][j] - mu; vs += d * d; }
; #pragma unroll
;       for (int x = 1; x < 16; x <<= 1) vs += shflx(vs, x, lane);
;       const float rsd = rsqrtf(vs * (1.f / 256.f) + 1e-5f);
;       const size_t ro = (size_t)(row0 + wave * 16 + fq * 4 + j) * DM + h * 256 + fr * 16;
;       const bf16x8 s0 = *(const bf16x8*)(p.sg + ro), s1 = *(const bf16x8*)(p.sg + ro + 8);
;       bf16x8 y0, y1;
; #pragma unroll
;       for (int et = 0; et < 8; ++et) {
;         y0[et] = (short)f2bf(bf2f((u16)s0[et]) * ((o[et][j] - mu) * rsd * gv[et]));
;         y1[et] = (short)f2bf(bf2f((u16)s1[et]) * ((o[et + 8][j] - mu) * rsd * gv[et + 8]));
;       }
;       *(bf16x8*)(p.y + ro) = y0; *(bf16x8*)(p.y + ro + 8) = y1;
;     }
	v_pk_add_f32 v[42:43], v[42:43], v[46:47]
	ds_bpermute_b32 v47, v94, v43
	ds_bpermute_b32 v46, v94, v42
	s_waitcnt vmcnt(0)
	v_and_b32_e32 v53, 0xffff0000, v100
	v_lshlrev_b32_e32 v52, 16, v100
	v_and_b32_e32 v55, 0xffff0000, v101
	v_lshlrev_b32_e32 v54, 16, v101
	s_waitcnt lgkmcnt(0)
	v_pk_add_f32 v[42:43], v[42:43], v[46:47]
	ds_bpermute_b32 v47, v23, v43
	ds_bpermute_b32 v46, v23, v42
	v_ashrrev_i32_e32 v23, 31, v22
	v_lshlrev_b64 v[22:23], 10, v[22:23]
	v_or3_b32 v22, v22, v98, s96
	v_lshlrev_b64 v[74:75], 1, v[22:23]
	s_waitcnt lgkmcnt(0)
	v_pk_add_f32 v[20:21], v[42:43], v[46:47]
	ds_bpermute_b32 v43, v0, v21
	ds_bpermute_b32 v42, v0, v20
	v_lshl_add_u64 v[46:47], s[14:15], 0, v[26:27]
	v_and_b32_e32 v57, 0xffff0000, v102
	v_lshlrev_b32_e32 v56, 16, v102
	v_and_b32_e32 v73, 0xffff0000, v103
	s_waitcnt lgkmcnt(0)
	v_pk_add_f32 v[20:21], v[20:21], v[42:43]
	v_lshlrev_b32_e32 v72, 16, v103
	v_pk_fma_f32 v[42:43], v[20:21], s[38:39], v[24:25] op_sel_hi:[1,0,0]
	v_lshl_add_u64 v[80:81], s[6:7], 0, v[74:75]
	v_mul_f32_e32 v0, 0x4b800000, v43
	v_cmp_gt_f32_e32 vcc, s35, v43
	s_nop 1
	v_cndmask_b32_e32 v0, v43, v0, vcc
	v_rsq_f32_e32 v0, v0
	s_nop 0
	v_mul_f32_e32 v20, 0x45800000, v0
	v_cndmask_b32_e32 v0, v0, v20, vcc
	v_pk_mul_f32 v[22:23], v[30:31], v[0:1] op_sel_hi:[1,0]
	v_pk_mul_f32 v[20:21], v[58:59], v[0:1] op_sel_hi:[1,0]
	v_pk_mul_f32 v[22:23], v[6:7], v[22:23]
	v_pk_mul_f32 v[20:21], v[14:15], v[20:21]
	v_pk_mul_f32 v[22:23], v[22:23], v[28:29]
	v_pk_mul_f32 v[20:21], v[20:21], v[52:53]
	v_cvt_pk_bf16_f32 v24, v22, v23
	v_pk_mul_f32 v[22:23], v[62:63], v[0:1] op_sel_hi:[1,0]
	v_cvt_pk_bf16_f32 v20, v20, v21
	v_pk_mul_f32 v[22:23], v[16:17], v[22:23]
	v_pk_mul_f32 v[18:19], v[18:19], v[0:1] op_sel_hi:[1,0]
	v_pk_mul_f32 v[22:23], v[22:23], v[54:55]
	v_pk_mul_f32 v[18:19], v[2:3], v[18:19]
	v_cvt_pk_bf16_f32 v21, v22, v23
	v_pk_mul_f32 v[22:23], v[32:33], v[0:1] op_sel_hi:[1,0]
	v_pk_mul_f32 v[18:19], v[18:19], v[48:49]
	v_pk_mul_f32 v[22:23], v[8:9], v[22:23]
	v_cvt_pk_bf16_f32 v26, v18, v19
	v_pk_mul_f32 v[22:23], v[22:23], v[34:35]
	v_pk_mul_f32 v[18:19], v[38:39], v[0:1] op_sel_hi:[1,0]
	v_cvt_pk_bf16_f32 v25, v22, v23
	v_pk_mul_f32 v[22:23], v[66:67], v[0:1] op_sel_hi:[1,0]
	v_pk_mul_f32 v[18:19], v[12:13], v[18:19]
	v_pk_mul_f32 v[22:23], v[10:11], v[22:23]
	v_pk_mul_f32 v[18:19], v[18:19], v[72:73]
	v_pk_mul_f32 v[22:23], v[22:23], v[56:57]
	v_cmp_gt_f32_e32 vcc, s35, v42
	v_cvt_pk_bf16_f32 v22, v22, v23
	v_cvt_pk_bf16_f32 v23, v18, v19
	v_pk_mul_f32 v[18:19], v[50:51], v[0:1] op_sel_hi:[1,0]
	v_mul_f32_e32 v0, 0x4b800000, v42
	v_pk_mul_f32 v[18:19], v[4:5], v[18:19]
	v_cndmask_b32_e32 v0, v42, v0, vcc
	v_pk_mul_f32 v[18:19], v[18:19], v[68:69]
	v_rsq_f32_e32 v0, v0
	v_cvt_pk_bf16_f32 v27, v18, v19
	global_store_dwordx4 v[46:47], v[20:23], off
	global_store_dwordx4 v[46:47], v[24:27], off offset:16
	global_load_dwordx4 v[18:21], v[80:81], off offset:16
	s_nop 0
	global_load_dwordx4 v[22:25], v[80:81], off
	s_waitcnt vmcnt(1)
	v_and_b32_e32 v27, 0xffff0000, v18
	s_waitcnt vmcnt(0)
	v_and_b32_e32 v31, 0xffff0000, v22
	v_lshlrev_b32_e32 v30, 16, v22
	v_and_b32_e32 v33, 0xffff0000, v23
	v_lshlrev_b32_e32 v32, 16, v23
	v_and_b32_e32 v23, 0xffff0000, v24
	v_lshlrev_b32_e32 v22, 16, v24
	v_mul_f32_e32 v24, 0x45800000, v0
	v_cndmask_b32_e32 v0, v0, v24, vcc
	v_lshlrev_b32_e32 v26, 16, v18
	v_and_b32_e32 v29, 0xffff0000, v19
	v_lshlrev_b32_e32 v28, 16, v19
	v_and_b32_e32 v19, 0xffff0000, v20
	v_lshlrev_b32_e32 v18, 16, v20
	v_and_b32_e32 v35, 0xffff0000, v21
	v_lshlrev_b32_e32 v34, 16, v21
	v_and_b32_e32 v21, 0xffff0000, v25
	v_lshlrev_b32_e32 v20, 16, v25
	v_pk_mul_f32 v[24:25], v[76:77], v[0:1] op_sel_hi:[1,0]
	s_nop 0
	v_pk_mul_f32 v[14:15], v[14:15], v[24:25]
	v_pk_mul_f32 v[24:25], v[70:71], v[0:1] op_sel_hi:[1,0]
	v_pk_mul_f32 v[14:15], v[14:15], v[30:31]
	v_pk_mul_f32 v[6:7], v[6:7], v[24:25]
	v_pk_mul_f32 v[24:25], v[78:79], v[0:1] op_sel_hi:[1,0]
	v_cvt_pk_bf16_f32 v14, v14, v15
	v_pk_mul_f32 v[16:17], v[16:17], v[24:25]
	v_pk_mul_f32 v[6:7], v[6:7], v[26:27]
	v_pk_mul_f32 v[16:17], v[16:17], v[32:33]
	v_cvt_pk_bf16_f32 v6, v6, v7
	v_cvt_pk_bf16_f32 v15, v16, v17
	v_pk_mul_f32 v[16:17], v[60:61], v[0:1] op_sel_hi:[1,0]
	s_nop 0
	v_pk_mul_f32 v[8:9], v[8:9], v[16:17]
	s_nop 0
	v_pk_mul_f32 v[8:9], v[8:9], v[28:29]
	s_nop 0
	v_cvt_pk_bf16_f32 v7, v8, v9
	v_pk_mul_f32 v[8:9], v[64:65], v[0:1] op_sel_hi:[1,0]
	s_nop 0
	v_pk_mul_f32 v[8:9], v[10:11], v[8:9]
	s_nop 0
	v_pk_mul_f32 v[8:9], v[8:9], v[22:23]
	s_nop 0
	v_cvt_pk_bf16_f32 v16, v8, v9
	v_pk_mul_f32 v[8:9], v[44:45], v[0:1] op_sel_hi:[1,0]
	s_nop 0
	v_pk_mul_f32 v[2:3], v[2:3], v[8:9]
	s_nop 0
	v_pk_mul_f32 v[2:3], v[2:3], v[18:19]
	s_nop 0
	v_cvt_pk_bf16_f32 v8, v2, v3
	v_pk_mul_f32 v[2:3], v[40:41], v[0:1] op_sel_hi:[1,0]
	s_nop 0
	v_pk_mul_f32 v[2:3], v[12:13], v[2:3]
	s_nop 0
	v_pk_mul_f32 v[2:3], v[2:3], v[20:21]
	s_nop 0
	v_cvt_pk_bf16_f32 v17, v2, v3
	v_pk_mul_f32 v[2:3], v[36:37], v[0:1] op_sel_hi:[1,0]
	s_nop 0
	v_pk_mul_f32 v[2:3], v[4:5], v[2:3]
	s_nop 0
	v_pk_mul_f32 v[2:3], v[2:3], v[34:35]
	s_nop 0
	v_cvt_pk_bf16_f32 v9, v2, v3
	v_lshl_add_u64 v[2:3], s[14:15], 0, v[74:75]
	global_store_dwordx4 v[2:3], v[14:17], off
	global_store_dwordx4 v[2:3], v[6:9], off offset:16
	s_cbranch_scc1 .LBB0_275
